# combo14 + Resid epilogue: remaining four second-half residual-row loads issued mid first-half into already-consumed first-batch registers; second-half wait becomes vmcnt(6)
# speedup vs baseline: 1.0036x; 1.0015x over previous
.LBB0_353:
	s_or_b64 exec, exec, s[34:35]
	v_lshlrev_b32_e32 v114, 16, v150
	s_waitcnt lgkmcnt(0)
	v_and_b32_e32 v115, 0xffff0000, v150
	v_lshlrev_b32_e32 v118, 16, v152
	v_and_b32_e32 v119, 0xffff0000, v152
	v_lshlrev_b32_e32 v120, 16, v153
	v_and_b32_e32 v121, 0xffff0000, v153
	v_lshlrev_b32_e32 v116, 16, v151
	v_and_b32_e32 v117, 0xffff0000, v151
	v_pk_fma_f32 v[110:111], v[196:197], v[110:111], v[114:115]
	v_pk_fma_f32 v[114:115], v[194:195], v[108:109], v[120:121]
	v_pk_fma_f32 v[108:109], v[196:197], v[106:107], v[118:119]
	v_pk_fma_f32 v[112:113], v[194:195], v[112:113], v[116:117]
	v_pk_mul_f32 v[106:107], v[108:109], v[108:109]
	v_pk_mul_f32 v[116:117], v[114:115], v[114:115]
	v_pk_fma_f32 v[106:107], v[110:111], v[110:111], v[106:107]
	v_pk_fma_f32 v[116:117], v[112:113], v[112:113], v[116:117]
	v_add_f32_e32 v106, v106, v107
	v_add_f32_e32 v107, v116, v117
	v_add_f32_e32 v118, v106, v107
	v_cvt_pk_bf16_f32 v106, v110, v111
	v_cvt_pk_bf16_f32 v107, v112, v113
	v_cvt_pk_bf16_f32 v108, v108, v109
	v_cvt_pk_bf16_f32 v109, v114, v115
	v_lshlrev_b32_e32 v110, 16, v146
	v_and_b32_e32 v111, 0xffff0000, v146
	v_lshlrev_b32_e32 v112, 16, v147
	v_and_b32_e32 v113, 0xffff0000, v147
	v_lshlrev_b32_e32 v114, 16, v148
	v_and_b32_e32 v115, 0xffff0000, v148
	v_lshlrev_b32_e32 v116, 16, v149
	v_and_b32_e32 v117, 0xffff0000, v149
	v_add_u32_e32 v184, 0xa0, v204
	v_ashrrev_i32_e32 v185, 31, v184
	v_lshlrev_b64 v[184:185], 11, v[184:185]
	v_lshl_add_u64 v[184:185], v[158:159], 0, v[184:185]
	global_load_dwordx4 v[172:175], v[184:185], off
	global_load_dwordx4 v[154:157], v[184:185], off offset:256
	v_add_u32_e32 v242, 0xb0, v204
	v_ashrrev_i32_e32 v243, 31, v242
	v_lshlrev_b64 v[242:243], 11, v[242:243]
	v_lshl_add_u64 v[242:243], v[158:159], 0, v[242:243]
	global_load_dwordx4 v[150:153], v[242:243], off
	global_load_dwordx4 v[146:149], v[242:243], off offset:256
	v_pk_fma_f32 v[102:103], v[196:197], v[102:103], v[110:111]
	v_pk_fma_f32 v[104:105], v[194:195], v[104:105], v[112:113]
	v_pk_fma_f32 v[110:111], v[194:195], v[100:101], v[116:117]
	v_pk_fma_f32 v[112:113], v[196:197], v[98:99], v[114:115]
	v_pk_mul_f32 v[100:101], v[110:111], v[110:111]
	v_pk_mul_f32 v[98:99], v[112:113], v[112:113]
	v_pk_fma_f32 v[100:101], v[104:105], v[104:105], v[100:101]
	v_pk_fma_f32 v[98:99], v[102:103], v[102:103], v[98:99]
	s_nop 0
	v_add_f32_e32 v98, v98, v99
	v_add_f32_e32 v99, v100, v101
	v_add_f32_e32 v98, v98, v99
	v_add_f32_e32 v101, v118, v98
	ds_bpermute_b32 v116, v171, v101
	v_lshl_add_u64 v[98:99], s[26:27], 0, v[164:165]
	v_lshl_add_u64 v[114:115], v[202:203], 1, v[98:99]
	v_cvt_pk_bf16_f32 v100, v102, v103
	v_cvt_pk_bf16_f32 v102, v112, v113
	s_waitcnt lgkmcnt(0)
	v_add_f32_e32 v98, v101, v116
	ds_bpermute_b32 v99, v170, v98
	v_cvt_pk_bf16_f32 v101, v104, v105
	v_cvt_pk_bf16_f32 v103, v110, v111
	global_store_dwordx4 v[114:115], v[106:109], off
	global_store_dwordx4 v[114:115], v[100:103], off offset:256
	s_and_saveexec_b64 s[34:35], s[6:7]
	s_cbranch_execz .LBB0_355
	v_lshlrev_b64 v[100:101], 6, v[210:211]
	v_lshl_add_u64 v[100:101], s[24:25], 0, v[100:101]
	v_lshl_add_u64 v[100:101], s[30:31], 2, v[100:101]
	s_lshl_b32 s84, s47, 2
	v_lshl_add_u64 v[100:101], v[100:101], 0, s[84:85]
	s_waitcnt lgkmcnt(0)
	v_add_f32_e32 v98, v98, v99
	global_store_dword v[100:101], v98, off

.LBB0_359:
	s_or_b64 exec, exec, s[34:35]
	v_add_u32_e32 v106, 0x80, v204
	v_ashrrev_i32_e32 v107, 31, v106
	v_lshlrev_b64 v[112:113], 11, v[106:107]
	s_waitcnt lgkmcnt(0)
	v_lshl_add_u64 v[66:67], v[158:159], 0, v[112:113]
	v_add_u32_e32 v102, 0x90, v204
	v_ashrrev_i32_e32 v103, 31, v102
	v_add_u32_e32 v98, 0xa0, v204
	v_lshlrev_b64 v[104:105], 11, v[102:103]
	v_ashrrev_i32_e32 v99, 31, v98
	v_add_u32_e32 v94, 0xb0, v204
	v_lshl_add_u64 v[66:67], v[158:159], 0, v[104:105]
	v_lshlrev_b64 v[100:101], 11, v[98:99]
	v_ashrrev_i32_e32 v95, 31, v94
	v_lshl_add_u64 v[66:67], v[158:159], 0, v[100:101]
	v_lshlrev_b64 v[96:97], 11, v[94:95]
	v_lshl_add_u64 v[66:67], v[158:159], 0, v[96:97]
	s_nop 0
	v_mov_b32_e32 v195, v194
	s_waitcnt vmcnt(6)
	v_lshlrev_b32_e32 v114, 16, v212
	v_and_b32_e32 v115, 0xffff0000, v212
	v_lshlrev_b32_e32 v108, 16, v213
	v_and_b32_e32 v109, 0xffff0000, v213
	v_lshlrev_b32_e32 v116, 16, v214
	v_and_b32_e32 v117, 0xffff0000, v214
	v_lshlrev_b32_e32 v110, 16, v215
	v_and_b32_e32 v111, 0xffff0000, v215
	v_pk_fma_f32 v[64:65], v[194:195], v[64:65], v[108:109]
	v_pk_fma_f32 v[108:109], v[194:195], v[60:61], v[110:111]
	v_pk_fma_f32 v[60:61], v[196:197], v[58:59], v[116:117]
	v_pk_fma_f32 v[62:63], v[196:197], v[62:63], v[114:115]
	v_pk_mul_f32 v[58:59], v[60:61], v[60:61]
	v_pk_mul_f32 v[110:111], v[108:109], v[108:109]
	v_pk_fma_f32 v[58:59], v[62:63], v[62:63], v[58:59]
	v_pk_fma_f32 v[110:111], v[64:65], v[64:65], v[110:111]
	v_add_f32_e32 v58, v58, v59
	v_add_f32_e32 v59, v110, v111
	v_add_f32_e32 v110, v58, v59
	v_cvt_pk_bf16_f32 v58, v62, v63
	v_lshl_add_u64 v[62:63], s[26:27], 0, v[112:113]
	v_cvt_pk_bf16_f32 v59, v64, v65
	v_cvt_pk_bf16_f32 v60, v60, v61
	v_cvt_pk_bf16_f32 v61, v108, v109
	v_lshl_add_u64 v[62:63], v[202:203], 1, v[62:63]
	global_store_dwordx4 v[62:63], v[58:61], off
	s_waitcnt vmcnt(7)
	v_lshlrev_b32_e32 v64, 16, v218
	v_and_b32_e32 v65, 0xffff0000, v218
	v_lshlrev_b32_e32 v58, 16, v216
	v_and_b32_e32 v59, 0xffff0000, v216
	v_lshlrev_b32_e32 v60, 16, v217
	v_and_b32_e32 v61, 0xffff0000, v217
	v_lshlrev_b32_e32 v90, 16, v219
	v_and_b32_e32 v91, 0xffff0000, v219
	v_pk_fma_f32 v[54:55], v[196:197], v[54:55], v[58:59]
	v_pk_fma_f32 v[58:59], v[194:195], v[52:53], v[90:91]
	v_pk_fma_f32 v[52:53], v[196:197], v[50:51], v[64:65]
	v_pk_fma_f32 v[56:57], v[194:195], v[56:57], v[60:61]
	v_pk_mul_f32 v[50:51], v[52:53], v[52:53]
	v_pk_mul_f32 v[60:61], v[58:59], v[58:59]
	v_pk_fma_f32 v[50:51], v[54:55], v[54:55], v[50:51]
	v_pk_fma_f32 v[60:61], v[56:57], v[56:57], v[60:61]
	v_add_f32_e32 v50, v50, v51
	v_add_f32_e32 v51, v60, v61
	v_add_f32_e32 v50, v50, v51
	v_add_f32_e32 v60, v110, v50
	v_cvt_pk_bf16_f32 v50, v54, v55
	v_cvt_pk_bf16_f32 v51, v56, v57
	v_cvt_pk_bf16_f32 v52, v52, v53
	v_cvt_pk_bf16_f32 v53, v58, v59
	global_store_dwordx4 v[62:63], v[50:53], off offset:256
	ds_bpermute_b32 v50, v171, v60
	s_waitcnt lgkmcnt(0)
	v_add_f32_e32 v50, v60, v50
	ds_bpermute_b32 v51, v170, v50
	s_and_saveexec_b64 s[34:35], s[6:7]
	s_cbranch_execz .LBB0_361
	v_lshlrev_b64 v[52:53], 6, v[106:107]
	v_lshl_add_u64 v[52:53], s[24:25], 0, v[52:53]
	v_lshl_add_u64 v[52:53], s[30:31], 2, v[52:53]
	s_lshl_b32 s84, s47, 2
	v_lshl_add_u64 v[52:53], v[52:53], 0, s[84:85]
	s_waitcnt lgkmcnt(0)
	v_add_f32_e32 v50, v50, v51
	global_store_dword v[52:53], v50, off

.LBB0_363:
	s_or_b64 exec, exec, s[34:35]
	s_waitcnt vmcnt(7)
	v_lshlrev_b32_e32 v34, 16, v172
	s_waitcnt lgkmcnt(0)
	v_and_b32_e32 v35, 0xffff0000, v172
	v_lshlrev_b32_e32 v38, 16, v174
	v_and_b32_e32 v39, 0xffff0000, v174
	v_lshlrev_b32_e32 v40, 16, v175
	v_and_b32_e32 v41, 0xffff0000, v175
	v_mov_b32_e32 v195, v194
	v_lshlrev_b32_e32 v36, 16, v173
	v_and_b32_e32 v37, 0xffff0000, v173
	v_pk_fma_f32 v[30:31], v[196:197], v[30:31], v[34:35]
	v_pk_fma_f32 v[34:35], v[194:195], v[28:29], v[40:41]
	v_pk_fma_f32 v[28:29], v[196:197], v[26:27], v[38:39]
	v_pk_fma_f32 v[32:33], v[194:195], v[32:33], v[36:37]
	v_pk_mul_f32 v[26:27], v[28:29], v[28:29]
	v_pk_mul_f32 v[36:37], v[34:35], v[34:35]
	v_pk_fma_f32 v[26:27], v[30:31], v[30:31], v[26:27]
	v_pk_fma_f32 v[36:37], v[32:33], v[32:33], v[36:37]
	v_add_f32_e32 v26, v26, v27
	v_add_f32_e32 v27, v36, v37
	v_add_f32_e32 v38, v26, v27
	v_cvt_pk_bf16_f32 v26, v30, v31
	v_cvt_pk_bf16_f32 v27, v32, v33
	v_cvt_pk_bf16_f32 v28, v28, v29
	v_cvt_pk_bf16_f32 v29, v34, v35
	s_waitcnt vmcnt(6)
	v_lshlrev_b32_e32 v30, 16, v154
	v_and_b32_e32 v31, 0xffff0000, v154
	v_lshlrev_b32_e32 v32, 16, v155
	v_and_b32_e32 v33, 0xffff0000, v155
	v_lshlrev_b32_e32 v34, 16, v156
	v_and_b32_e32 v35, 0xffff0000, v156
	v_lshlrev_b32_e32 v36, 16, v157
	v_and_b32_e32 v37, 0xffff0000, v157
	v_pk_fma_f32 v[22:23], v[196:197], v[22:23], v[30:31]
	v_pk_fma_f32 v[24:25], v[194:195], v[24:25], v[32:33]
	v_pk_fma_f32 v[30:31], v[194:195], v[20:21], v[36:37]
	v_pk_fma_f32 v[32:33], v[196:197], v[18:19], v[34:35]
	v_pk_mul_f32 v[20:21], v[30:31], v[30:31]
	v_pk_mul_f32 v[18:19], v[32:33], v[32:33]
	v_pk_fma_f32 v[20:21], v[24:25], v[24:25], v[20:21]
	v_pk_fma_f32 v[18:19], v[22:23], v[22:23], v[18:19]
	s_nop 0
	v_add_f32_e32 v18, v18, v19
	v_add_f32_e32 v19, v20, v21
	v_add_f32_e32 v18, v18, v19
	v_add_f32_e32 v21, v38, v18
	ds_bpermute_b32 v36, v171, v21
	v_lshl_add_u64 v[18:19], s[26:27], 0, v[100:101]
	v_lshl_add_u64 v[34:35], v[202:203], 1, v[18:19]
	v_cvt_pk_bf16_f32 v20, v22, v23
	v_cvt_pk_bf16_f32 v22, v32, v33
	s_waitcnt lgkmcnt(0)
	v_add_f32_e32 v18, v21, v36
	ds_bpermute_b32 v19, v170, v18
	v_cvt_pk_bf16_f32 v21, v24, v25
	v_cvt_pk_bf16_f32 v23, v30, v31
	global_store_dwordx4 v[34:35], v[26:29], off
	global_store_dwordx4 v[34:35], v[20:23], off offset:256
	s_and_saveexec_b64 s[34:35], s[6:7]
	s_cbranch_execz .LBB0_365
	v_lshlrev_b64 v[20:21], 6, v[98:99]
	v_lshl_add_u64 v[20:21], s[24:25], 0, v[20:21]
	v_lshl_add_u64 v[20:21], s[30:31], 2, v[20:21]
	s_lshl_b32 s84, s47, 2
	v_lshl_add_u64 v[20:21], v[20:21], 0, s[84:85]
	s_waitcnt lgkmcnt(0)
	v_add_f32_e32 v18, v18, v19
	global_store_dword v[20:21], v18, off
.LBB0_365:
	s_or_b64 exec, exec, s[34:35]
	s_waitcnt vmcnt(7)
	v_lshlrev_b32_e32 v18, 16, v150
	s_waitcnt lgkmcnt(0)
	v_and_b32_e32 v19, 0xffff0000, v150
	v_lshlrev_b32_e32 v22, 16, v152
	v_and_b32_e32 v23, 0xffff0000, v152
	v_lshlrev_b32_e32 v24, 16, v153
	v_and_b32_e32 v25, 0xffff0000, v153
	v_lshlrev_b32_e32 v20, 16, v151
	v_and_b32_e32 v21, 0xffff0000, v151
	v_pk_fma_f32 v[14:15], v[196:197], v[14:15], v[18:19]
	v_pk_fma_f32 v[18:19], v[194:195], v[12:13], v[24:25]
	v_pk_fma_f32 v[12:13], v[196:197], v[10:11], v[22:23]
	v_pk_fma_f32 v[16:17], v[194:195], v[16:17], v[20:21]
	v_pk_mul_f32 v[10:11], v[12:13], v[12:13]
	v_pk_mul_f32 v[20:21], v[18:19], v[18:19]
	v_pk_fma_f32 v[10:11], v[14:15], v[14:15], v[10:11]
	v_pk_fma_f32 v[20:21], v[16:17], v[16:17], v[20:21]
	v_add_f32_e32 v10, v10, v11
	v_add_f32_e32 v11, v20, v21
	v_add_f32_e32 v22, v10, v11
	v_cvt_pk_bf16_f32 v10, v14, v15
	v_cvt_pk_bf16_f32 v11, v16, v17
	v_cvt_pk_bf16_f32 v12, v12, v13
	v_cvt_pk_bf16_f32 v13, v18, v19
	s_waitcnt vmcnt(6)
	v_lshlrev_b32_e32 v14, 16, v146
	v_and_b32_e32 v15, 0xffff0000, v146
	v_lshlrev_b32_e32 v16, 16, v147
	v_and_b32_e32 v17, 0xffff0000, v147
	v_lshlrev_b32_e32 v18, 16, v148
	v_and_b32_e32 v19, 0xffff0000, v148
	v_lshlrev_b32_e32 v20, 16, v149
	v_and_b32_e32 v21, 0xffff0000, v149
	v_pk_fma_f32 v[6:7], v[196:197], v[6:7], v[14:15]
	v_pk_fma_f32 v[8:9], v[194:195], v[8:9], v[16:17]
	v_pk_fma_f32 v[14:15], v[194:195], v[4:5], v[20:21]
	v_pk_fma_f32 v[16:17], v[196:197], v[2:3], v[18:19]
	v_pk_mul_f32 v[4:5], v[14:15], v[14:15]
	v_pk_mul_f32 v[2:3], v[16:17], v[16:17]
	v_pk_fma_f32 v[4:5], v[8:9], v[8:9], v[4:5]
	v_pk_fma_f32 v[2:3], v[6:7], v[6:7], v[2:3]
	s_nop 0
	v_add_f32_e32 v2, v2, v3
	v_add_f32_e32 v3, v4, v5
	v_add_f32_e32 v2, v2, v3
	v_add_f32_e32 v5, v22, v2
	ds_bpermute_b32 v20, v171, v5
	v_lshl_add_u64 v[2:3], s[26:27], 0, v[96:97]
	v_lshl_add_u64 v[18:19], v[202:203], 1, v[2:3]
	v_cvt_pk_bf16_f32 v4, v6, v7
	v_cvt_pk_bf16_f32 v6, v16, v17
	s_waitcnt lgkmcnt(0)
	v_add_f32_e32 v2, v5, v20
	ds_bpermute_b32 v3, v170, v2
	v_cvt_pk_bf16_f32 v5, v8, v9
	v_cvt_pk_bf16_f32 v7, v14, v15
	global_store_dwordx4 v[18:19], v[10:13], off
	global_store_dwordx4 v[18:19], v[4:7], off offset:256
	s_and_saveexec_b64 s[34:35], s[6:7]
	s_cbranch_execz .LBB0_322
	v_lshlrev_b64 v[4:5], 6, v[94:95]
	v_lshl_add_u64 v[4:5], s[24:25], 0, v[4:5]
	v_lshl_add_u64 v[4:5], s[30:31], 2, v[4:5]
	s_lshl_b32 s84, s47, 2
	v_lshl_add_u64 v[4:5], v[4:5], 0, s[84:85]
	s_waitcnt lgkmcnt(0)
	v_add_f32_e32 v2, v2, v3
	global_store_dword v[4:5], v2, off
	s_branch .LBB0_322
